# pool GEMM epilogue (odd layers): scale loads of each 8-tile group issued up front
# speedup vs baseline: 1.0152x; 1.0030x over previous
.LBB0_542:
	s_or_b64 exec, exec, s[8:9]
	v_sub_u32_e32 v122, v146, v145
	v_cvt_f32_i32_e32 v122, v122
	v_sub_u32_e32 v0, v142, v0
	v_cvt_f32_i32_e32 v0, v0
	v_div_scale_f32 v123, s[0:1], v122, v122, 1.0
	v_rcp_f32_e32 v145, v123
	s_nop 0
	v_fma_f32 v146, -v123, v145, 1.0
	v_fmac_f32_e32 v145, v146, v145
	v_div_scale_f32 v146, vcc, 1.0, v122, 1.0
	v_mul_f32_e32 v147, v146, v145
	v_fma_f32 v148, -v123, v147, v146
	v_fmac_f32_e32 v147, v148, v145
	v_fma_f32 v123, -v123, v147, v146
	v_div_fmas_f32 v123, v123, v145, v147
	v_div_fixup_f32 v122, v123, v122, 1.0
	s_waitcnt vmcnt(1)
	v_lshlrev_b32_e32 v146, 16, v53
	v_and_b32_e32 v147, 0xffff0000, v53
	v_pk_fma_f32 v[130:131], v[122:123], v[130:131], v[146:147] op_sel_hi:[0,1,1] neg_lo:[0,0,1] neg_hi:[0,0,1]
	v_cvt_pk_bf16_f32 v53, v130, v131
	v_lshlrev_b32_e32 v130, 16, v50
	v_and_b32_e32 v131, 0xffff0000, v50
	v_pk_fma_f32 v[128:129], v[122:123], v[128:129], v[130:131] op_sel_hi:[0,1,1] neg_lo:[0,0,1] neg_hi:[0,0,1]
	v_cvt_pk_bf16_f32 v50, v128, v129
	v_lshlrev_b32_e32 v128, 16, v51
	v_and_b32_e32 v129, 0xffff0000, v51
	v_pk_fma_f32 v[126:127], v[122:123], v[126:127], v[128:129] op_sel_hi:[0,1,1] neg_lo:[0,0,1] neg_hi:[0,0,1]
	v_cvt_pk_bf16_f32 v51, v126, v127
	v_lshlrev_b32_e32 v126, 16, v52
	v_and_b32_e32 v127, 0xffff0000, v52
	v_pk_fma_f32 v[122:123], v[122:123], v[124:125], v[126:127] op_sel_hi:[0,1,1] neg_lo:[0,0,1] neg_hi:[0,0,1]
	v_cvt_pk_bf16_f32 v52, v122, v123
	v_div_scale_f32 v122, s[0:1], v0, v0, 1.0
	v_rcp_f32_e32 v123, v122
	s_nop 0
	v_fma_f32 v124, -v122, v123, 1.0
	v_fmac_f32_e32 v123, v124, v123
	v_div_scale_f32 v124, vcc, 1.0, v0, 1.0
	v_mul_f32_e32 v125, v124, v123
	v_fma_f32 v126, -v122, v125, v124
	v_fmac_f32_e32 v125, v126, v123
	v_fma_f32 v122, -v122, v125, v124
	v_div_fmas_f32 v122, v122, v123, v125
	v_div_fixup_f32 v0, v122, v0, 1.0
	v_lshlrev_b32_e32 v122, 16, v57
	v_and_b32_e32 v123, 0xffff0000, v57
	v_pk_fma_f32 v[120:121], v[0:1], v[120:121], v[122:123] op_sel_hi:[0,1,1] neg_lo:[0,0,1] neg_hi:[0,0,1]
	v_cvt_pk_bf16_f32 v57, v120, v121
	v_lshlrev_b32_e32 v120, 16, v54
	v_and_b32_e32 v121, 0xffff0000, v54
	v_pk_fma_f32 v[118:119], v[0:1], v[118:119], v[120:121] op_sel_hi:[0,1,1] neg_lo:[0,0,1] neg_hi:[0,0,1]
	v_cvt_pk_bf16_f32 v54, v118, v119
	v_lshlrev_b32_e32 v118, 16, v55
	v_and_b32_e32 v119, 0xffff0000, v55
	v_pk_fma_f32 v[116:117], v[0:1], v[116:117], v[118:119] op_sel_hi:[0,1,1] neg_lo:[0,0,1] neg_hi:[0,0,1]
	v_cvt_pk_bf16_f32 v55, v116, v117
	v_lshlrev_b32_e32 v116, 16, v56
	v_and_b32_e32 v117, 0xffff0000, v56
	v_pk_fma_f32 v[114:115], v[0:1], v[114:115], v[116:117] op_sel_hi:[0,1,1] neg_lo:[0,0,1] neg_hi:[0,0,1]
	v_sub_u32_e32 v0, v141, v140
	v_cvt_f32_i32_e32 v0, v0
	v_cvt_pk_bf16_f32 v56, v114, v115
	v_div_scale_f32 v114, s[0:1], v0, v0, 1.0
	v_rcp_f32_e32 v115, v114
	s_nop 0
	v_fma_f32 v116, -v114, v115, 1.0
	v_fmac_f32_e32 v115, v116, v115
	v_div_scale_f32 v116, vcc, 1.0, v0, 1.0
	v_mul_f32_e32 v117, v116, v115
	v_fma_f32 v118, -v114, v117, v116
	v_fmac_f32_e32 v117, v118, v115
	v_fma_f32 v114, -v114, v117, v116
	v_div_fmas_f32 v114, v114, v115, v117
	v_div_fixup_f32 v0, v114, v0, 1.0
	v_lshlrev_b32_e32 v114, 16, v61
	v_and_b32_e32 v115, 0xffff0000, v61
	v_pk_fma_f32 v[110:111], v[0:1], v[110:111], v[114:115] op_sel_hi:[0,1,1] neg_lo:[0,0,1] neg_hi:[0,0,1]
	v_cvt_pk_bf16_f32 v61, v110, v111
	v_lshlrev_b32_e32 v110, 16, v58
	v_and_b32_e32 v111, 0xffff0000, v58
	v_pk_fma_f32 v[108:109], v[0:1], v[108:109], v[110:111] op_sel_hi:[0,1,1] neg_lo:[0,0,1] neg_hi:[0,0,1]
	v_cvt_pk_bf16_f32 v58, v108, v109
	v_lshlrev_b32_e32 v108, 16, v59
	v_and_b32_e32 v109, 0xffff0000, v59
	v_pk_fma_f32 v[106:107], v[0:1], v[106:107], v[108:109] op_sel_hi:[0,1,1] neg_lo:[0,0,1] neg_hi:[0,0,1]
	v_cvt_pk_bf16_f32 v59, v106, v107
	v_lshlrev_b32_e32 v106, 16, v60
	v_and_b32_e32 v107, 0xffff0000, v60
	v_pk_fma_f32 v[104:105], v[0:1], v[104:105], v[106:107] op_sel_hi:[0,1,1] neg_lo:[0,0,1] neg_hi:[0,0,1]
	v_sub_u32_e32 v0, v139, v138
	v_cvt_f32_i32_e32 v0, v0
	v_cvt_pk_bf16_f32 v60, v104, v105
	v_div_scale_f32 v104, s[0:1], v0, v0, 1.0
	v_rcp_f32_e32 v105, v104
	s_nop 0
	v_fma_f32 v106, -v104, v105, 1.0
	v_fmac_f32_e32 v105, v106, v105
	v_div_scale_f32 v106, vcc, 1.0, v0, 1.0
	v_mul_f32_e32 v107, v106, v105
	v_fma_f32 v108, -v104, v107, v106
	v_fmac_f32_e32 v107, v108, v105
	v_fma_f32 v104, -v104, v107, v106
	v_div_fmas_f32 v104, v104, v105, v107
	v_div_fixup_f32 v0, v104, v0, 1.0
	v_lshlrev_b32_e32 v104, 16, v46
	v_and_b32_e32 v105, 0xffff0000, v46
	v_pk_fma_f32 v[94:95], v[0:1], v[94:95], v[104:105] op_sel_hi:[0,1,1] neg_lo:[0,0,1] neg_hi:[0,0,1]
	v_cvt_pk_bf16_f32 v46, v94, v95
	v_lshlrev_b32_e32 v94, 16, v47
	v_and_b32_e32 v95, 0xffff0000, v47
	v_pk_fma_f32 v[92:93], v[0:1], v[92:93], v[94:95] op_sel_hi:[0,1,1] neg_lo:[0,0,1] neg_hi:[0,0,1]
	v_cvt_pk_bf16_f32 v47, v92, v93
	v_lshlrev_b32_e32 v92, 16, v48
	v_and_b32_e32 v93, 0xffff0000, v48
	v_pk_fma_f32 v[90:91], v[0:1], v[90:91], v[92:93] op_sel_hi:[0,1,1] neg_lo:[0,0,1] neg_hi:[0,0,1]
	v_cvt_pk_bf16_f32 v48, v90, v91
	v_lshlrev_b32_e32 v90, 16, v49
	v_and_b32_e32 v91, 0xffff0000, v49
	v_pk_fma_f32 v[88:89], v[0:1], v[88:89], v[90:91] op_sel_hi:[0,1,1] neg_lo:[0,0,1] neg_hi:[0,0,1]
	v_sub_u32_e32 v0, v137, v136
	v_cvt_f32_i32_e32 v0, v0
	v_cvt_pk_bf16_f32 v49, v88, v89
	v_div_scale_f32 v88, s[0:1], v0, v0, 1.0
	v_rcp_f32_e32 v89, v88
	s_nop 0
	v_fma_f32 v90, -v88, v89, 1.0
	v_fmac_f32_e32 v89, v90, v89
	v_div_scale_f32 v90, vcc, 1.0, v0, 1.0
	v_mul_f32_e32 v91, v90, v89
	v_fma_f32 v92, -v88, v91, v90
	v_fmac_f32_e32 v91, v92, v89
	v_fma_f32 v88, -v88, v91, v90
	v_div_fmas_f32 v88, v88, v89, v91
	v_div_fixup_f32 v0, v88, v0, 1.0
	v_lshlrev_b32_e32 v88, 16, v38
	v_and_b32_e32 v89, 0xffff0000, v38
	v_pk_fma_f32 v[84:85], v[0:1], v[84:85], v[88:89] op_sel_hi:[0,1,1] neg_lo:[0,0,1] neg_hi:[0,0,1]
	v_cvt_pk_bf16_f32 v38, v84, v85
	v_lshlrev_b32_e32 v84, 16, v39
	v_and_b32_e32 v85, 0xffff0000, v39
	v_pk_fma_f32 v[82:83], v[0:1], v[82:83], v[84:85] op_sel_hi:[0,1,1] neg_lo:[0,0,1] neg_hi:[0,0,1]
	v_cvt_pk_bf16_f32 v39, v82, v83
	v_lshlrev_b32_e32 v82, 16, v40
	v_and_b32_e32 v83, 0xffff0000, v40
	v_pk_fma_f32 v[80:81], v[0:1], v[80:81], v[82:83] op_sel_hi:[0,1,1] neg_lo:[0,0,1] neg_hi:[0,0,1]
	v_cvt_pk_bf16_f32 v40, v80, v81
	v_lshlrev_b32_e32 v80, 16, v41
	v_and_b32_e32 v81, 0xffff0000, v41
	v_pk_fma_f32 v[78:79], v[0:1], v[78:79], v[80:81] op_sel_hi:[0,1,1] neg_lo:[0,0,1] neg_hi:[0,0,1]
	v_sub_u32_e32 v0, v135, v134
	v_cvt_f32_i32_e32 v0, v0
	v_cvt_pk_bf16_f32 v41, v78, v79
	v_div_scale_f32 v78, s[0:1], v0, v0, 1.0
	v_rcp_f32_e32 v79, v78
	s_nop 0
	v_fma_f32 v80, -v78, v79, 1.0
	v_fmac_f32_e32 v79, v80, v79
	v_div_scale_f32 v80, vcc, 1.0, v0, 1.0
	v_mul_f32_e32 v81, v80, v79
	v_fma_f32 v82, -v78, v81, v80
	v_fmac_f32_e32 v81, v82, v79
	v_fma_f32 v78, -v78, v81, v80
	v_div_fmas_f32 v78, v78, v79, v81
	v_div_fixup_f32 v0, v78, v0, 1.0
	v_lshlrev_b32_e32 v78, 16, v30
	v_and_b32_e32 v79, 0xffff0000, v30
	v_pk_fma_f32 v[76:77], v[0:1], v[76:77], v[78:79] op_sel_hi:[0,1,1] neg_lo:[0,0,1] neg_hi:[0,0,1]
	v_cvt_pk_bf16_f32 v30, v76, v77
	v_lshlrev_b32_e32 v76, 16, v31
	v_and_b32_e32 v77, 0xffff0000, v31
	v_pk_fma_f32 v[74:75], v[0:1], v[74:75], v[76:77] op_sel_hi:[0,1,1] neg_lo:[0,0,1] neg_hi:[0,0,1]
	v_cvt_pk_bf16_f32 v31, v74, v75
	v_lshlrev_b32_e32 v74, 16, v32
	v_and_b32_e32 v75, 0xffff0000, v32
	v_pk_fma_f32 v[72:73], v[0:1], v[72:73], v[74:75] op_sel_hi:[0,1,1] neg_lo:[0,0,1] neg_hi:[0,0,1]
	v_cvt_pk_bf16_f32 v32, v72, v73
	v_lshlrev_b32_e32 v72, 16, v33
	v_and_b32_e32 v73, 0xffff0000, v33
	v_pk_fma_f32 v[70:71], v[0:1], v[70:71], v[72:73] op_sel_hi:[0,1,1] neg_lo:[0,0,1] neg_hi:[0,0,1]
	v_sub_u32_e32 v0, v133, v113
	v_cvt_f32_i32_e32 v0, v0
	v_cvt_pk_bf16_f32 v33, v70, v71
	v_ashrrev_i32_e32 v113, 31, v112
	v_div_scale_f32 v70, s[0:1], v0, v0, 1.0
	v_rcp_f32_e32 v71, v70
	s_nop 0
	v_fma_f32 v72, -v70, v71, 1.0
	v_fmac_f32_e32 v71, v72, v71
	v_div_scale_f32 v72, vcc, 1.0, v0, 1.0
	v_mul_f32_e32 v73, v72, v71
	v_fma_f32 v74, -v70, v73, v72
	v_fmac_f32_e32 v73, v74, v71
	v_fma_f32 v70, -v70, v73, v72
	v_div_fmas_f32 v70, v70, v71, v73
	v_div_fixup_f32 v0, v70, v0, 1.0
	v_lshlrev_b32_e32 v70, 16, v22
	v_and_b32_e32 v71, 0xffff0000, v22
	v_pk_fma_f32 v[68:69], v[0:1], v[68:69], v[70:71] op_sel_hi:[0,1,1] neg_lo:[0,0,1] neg_hi:[0,0,1]
	v_cvt_pk_bf16_f32 v22, v68, v69
	v_lshlrev_b32_e32 v68, 16, v23
	v_and_b32_e32 v69, 0xffff0000, v23
	v_pk_fma_f32 v[66:67], v[0:1], v[66:67], v[68:69] op_sel_hi:[0,1,1] neg_lo:[0,0,1] neg_hi:[0,0,1]
	v_cvt_pk_bf16_f32 v23, v66, v67
	v_lshlrev_b32_e32 v66, 16, v24
	v_and_b32_e32 v67, 0xffff0000, v24
	v_pk_fma_f32 v[64:65], v[0:1], v[64:65], v[66:67] op_sel_hi:[0,1,1] neg_lo:[0,0,1] neg_hi:[0,0,1]
	v_cvt_pk_bf16_f32 v24, v64, v65
	v_lshlrev_b32_e32 v64, 16, v25
	v_and_b32_e32 v65, 0xffff0000, v25
	v_pk_fma_f32 v[62:63], v[0:1], v[62:63], v[64:65] op_sel_hi:[0,1,1] neg_lo:[0,0,1] neg_hi:[0,0,1]
	v_sub_u32_e32 v0, v144, v143
	v_cvt_f32_i32_e32 v0, v0
	v_cvt_pk_bf16_f32 v25, v62, v63
	v_and_b32_e32 v66, 15, v132
	v_div_scale_f32 v62, s[0:1], v0, v0, 1.0
	v_rcp_f32_e32 v63, v62
	s_nop 0
	v_fma_f32 v64, -v62, v63, 1.0
	v_fmac_f32_e32 v63, v64, v63
	v_div_scale_f32 v64, vcc, 1.0, v0, 1.0
	v_mul_f32_e32 v65, v64, v63
	v_fma_f32 v67, -v62, v65, v64
	v_fmac_f32_e32 v65, v67, v63
	v_fma_f32 v62, -v62, v65, v64
	v_div_fmas_f32 v62, v62, v63, v65
	v_div_fixup_f32 v0, v62, v0, 1.0
	v_lshlrev_b64 v[62:63], 10, v[112:113]
	v_lshl_add_u64 v[62:63], v[86:87], 0, v[62:63]
	global_load_dwordx4 v[62:65], v[62:63], off offset:128
	v_lshrrev_b32_e32 v67, 3, v132
	s_barrier
	s_waitcnt vmcnt(0)
	v_lshlrev_b32_e32 v68, 16, v62
	v_and_b32_e32 v69, 0xffff0000, v62
	v_pk_fma_f32 v[68:69], v[0:1], v[102:103], v[68:69] op_sel_hi:[0,1,1] neg_lo:[0,0,1] neg_hi:[0,0,1]
	v_cvt_pk_bf16_f32 v62, v68, v69
	v_lshlrev_b32_e32 v68, 16, v63
	v_and_b32_e32 v69, 0xffff0000, v63
	v_pk_fma_f32 v[68:69], v[0:1], v[100:101], v[68:69] op_sel_hi:[0,1,1] neg_lo:[0,0,1] neg_hi:[0,0,1]
	v_cvt_pk_bf16_f32 v63, v68, v69
	v_lshlrev_b32_e32 v68, 16, v64
	v_and_b32_e32 v69, 0xffff0000, v64
	v_pk_fma_f32 v[68:69], v[0:1], v[98:99], v[68:69] op_sel_hi:[0,1,1] neg_lo:[0,0,1] neg_hi:[0,0,1]
	v_cvt_pk_bf16_f32 v64, v68, v69
	v_lshlrev_b32_e32 v68, 16, v65
	v_and_b32_e32 v69, 0xffff0000, v65
	v_pk_fma_f32 v[68:69], v[0:1], v[96:97], v[68:69] op_sel_hi:[0,1,1] neg_lo:[0,0,1] neg_hi:[0,0,1]
	v_lshlrev_b32_e32 v0, 4, v132
	v_and_b32_e32 v0, 0x70, v0
	v_add_u32_e32 v0, 0, v0
	v_mad_u64_u32 v[142:143], s[0:1], v67, s16, v[0:1]
	ds_write_b128 v142, v[22:25]
	ds_write_b128 v142, v[2:5] offset:18432
	v_add_u32_e32 v2, 0x100, v132
	v_lshrrev_b32_e32 v2, 3, v2
	v_mad_u64_u32 v[144:145], s[0:1], v2, s16, v[0:1]
	v_add_u32_e32 v2, 0x200, v132
	v_lshrrev_b32_e32 v2, 3, v2
	v_mad_u64_u32 v[146:147], s[0:1], v2, s16, v[0:1]
	v_add_u32_e32 v2, 0x300, v132
	v_lshrrev_b32_e32 v2, 3, v2
	v_mad_u64_u32 v[148:149], s[0:1], v2, s16, v[0:1]
	v_lshrrev_b32_e32 v0, 1, v132
	s_mov_b32 s0, 0xfffffe0
	v_and_or_b32 v0, v0, s0, v66
	v_and_b32_e32 v2, 48, v132
	v_add_u32_e32 v3, 0, v2
	v_mul_lo_u32 v0, v0, s16
	v_mul_u32_u24_e32 v4, 0x48, v66
	v_add_u32_e32 v143, v3, v0
	v_lshlrev_b32_e32 v4, 1, v4
	s_add_i32 s0, 0, 0xd800
	v_cvt_pk_bf16_f32 v65, v68, v69
	ds_write_b128 v144, v[30:33]
	ds_write_b128 v144, v[6:9] offset:18432
	ds_write_b128 v146, v[38:41]
	ds_write_b128 v146, v[10:13] offset:18432
	ds_write_b128 v148, v[46:49]
	ds_write_b128 v148, v[14:17] offset:18432
	s_waitcnt lgkmcnt(0)
	s_barrier
	v_add_u32_e32 v145, v3, v4
	v_add3_u32 v0, 0, v0, v2
	v_add3_u32 v147, 0, v4, v2
	v_add3_u32 v150, v4, s0, v2
	ds_read_b128 v[2:5], v143
	ds_read_b128 v[6:9], v143 offset:2304
	ds_read_b128 v[10:13], v145 offset:18432
	ds_read_b128 v[14:17], v145 offset:20736
	ds_read_b128 v[22:25], v145 offset:23040
	ds_read_b128 v[30:33], v145 offset:25344
	ds_read_b128 v[38:41], v145 offset:27648
	ds_read_b128 v[46:49], v145 offset:29952
	ds_read_b128 v[66:69], v145 offset:32256
	ds_read_b128 v[70:73], v145 offset:34560
	ds_read_b128 v[74:77], v0 offset:64
	ds_read_b128 v[78:81], v0 offset:2368
	ds_read_b128 v[82:85], v147 offset:18496
	ds_read_b128 v[86:89], v147 offset:20800
	ds_read_b128 v[90:93], v147 offset:23104
	ds_read_b128 v[94:97], v147 offset:25408
	ds_read_b128 v[98:101], v147 offset:27712
	ds_read_b128 v[102:105], v147 offset:30016
	ds_read_b128 v[106:109], v147 offset:32320
	ds_read_b128 v[110:113], v147 offset:34624
	v_add_u32_e32 v149, 0xd800, v145
	s_waitcnt lgkmcnt(14)
	v_mfma_f32_16x16x32_bf16 v[114:117], v[10:13], v[2:5], 0
	v_mfma_f32_16x16x32_bf16 v[10:13], v[10:13], v[6:9], 0
	v_mfma_f32_16x16x32_bf16 v[118:121], v[14:17], v[2:5], 0
	v_mfma_f32_16x16x32_bf16 v[14:17], v[14:17], v[6:9], 0
	v_mfma_f32_16x16x32_bf16 v[122:125], v[22:25], v[2:5], 0
	v_mfma_f32_16x16x32_bf16 v[22:25], v[22:25], v[6:9], 0
	v_mfma_f32_16x16x32_bf16 v[126:129], v[30:33], v[2:5], 0
	v_mfma_f32_16x16x32_bf16 v[30:33], v[30:33], v[6:9], 0
	s_waitcnt lgkmcnt(13)
	v_mfma_f32_16x16x32_bf16 v[130:133], v[38:41], v[2:5], 0
	v_mfma_f32_16x16x32_bf16 v[38:41], v[38:41], v[6:9], 0
	s_waitcnt lgkmcnt(12)
	v_mfma_f32_16x16x32_bf16 v[134:137], v[46:49], v[2:5], 0
	v_mfma_f32_16x16x32_bf16 v[46:49], v[46:49], v[6:9], 0
	s_waitcnt lgkmcnt(11)
	v_mfma_f32_16x16x32_bf16 v[138:141], v[66:69], v[2:5], 0
	v_mfma_f32_16x16x32_bf16 v[66:69], v[66:69], v[6:9], 0
	s_waitcnt lgkmcnt(10)
	v_mfma_f32_16x16x32_bf16 v[2:5], v[70:73], v[2:5], 0
	v_mfma_f32_16x16x32_bf16 v[6:9], v[70:73], v[6:9], 0
	s_waitcnt lgkmcnt(7)
	v_mfma_f32_16x16x32_bf16 v[70:73], v[82:85], v[74:77], v[114:117]
	v_mfma_f32_16x16x32_bf16 v[10:13], v[82:85], v[78:81], v[10:13]
	s_waitcnt lgkmcnt(6)
	v_mfma_f32_16x16x32_bf16 v[82:85], v[86:89], v[74:77], v[118:121]
	v_mfma_f32_16x16x32_bf16 v[14:17], v[86:89], v[78:81], v[14:17]
	s_waitcnt lgkmcnt(5)
	v_mfma_f32_16x16x32_bf16 v[86:89], v[90:93], v[74:77], v[122:125]
	v_mfma_f32_16x16x32_bf16 v[22:25], v[90:93], v[78:81], v[22:25]
	s_waitcnt lgkmcnt(4)
	v_mfma_f32_16x16x32_bf16 v[90:93], v[94:97], v[74:77], v[126:129]
	v_mfma_f32_16x16x32_bf16 v[30:33], v[94:97], v[78:81], v[30:33]
	s_waitcnt lgkmcnt(3)
	v_mfma_f32_16x16x32_bf16 v[94:97], v[98:101], v[74:77], v[130:133]
	v_mfma_f32_16x16x32_bf16 v[38:41], v[98:101], v[78:81], v[38:41]
	s_waitcnt lgkmcnt(2)
	v_mfma_f32_16x16x32_bf16 v[98:101], v[102:105], v[74:77], v[134:137]
	v_mfma_f32_16x16x32_bf16 v[46:49], v[102:105], v[78:81], v[46:49]
	s_waitcnt lgkmcnt(1)
	v_mfma_f32_16x16x32_bf16 v[102:105], v[106:109], v[74:77], v[138:141]
	v_mfma_f32_16x16x32_bf16 v[66:69], v[106:109], v[78:81], v[66:69]
	s_waitcnt lgkmcnt(0)
	v_mfma_f32_16x16x32_bf16 v[2:5], v[110:113], v[74:77], v[2:5]
	v_mfma_f32_16x16x32_bf16 v[6:9], v[110:113], v[78:81], v[6:9]
	ds_write_b128 v142, v[58:61] offset:36864
	ds_write_b128 v142, v[18:21] offset:55296
	ds_write_b128 v144, v[54:57] offset:36864
	ds_write_b128 v144, v[26:29] offset:55296
	ds_write_b128 v146, v[50:53] offset:36864
	ds_write_b128 v146, v[34:37] offset:55296
	ds_write_b128 v148, v[62:65] offset:36864
	ds_write_b128 v148, v[42:45] offset:55296
	s_waitcnt lgkmcnt(0)
	s_barrier
	ds_read_b128 v[18:21], v143 offset:36864
	ds_read_b128 v[26:29], v143 offset:39168
	ds_read_b128 v[34:37], v145 offset:55296
	ds_read_b128 v[42:45], v145 offset:57600
	ds_read_b128 v[50:53], v145 offset:59904
	ds_read_b128 v[54:57], v145 offset:62208
	ds_read_b128 v[58:61], v149 offset:11520
	ds_read_b128 v[62:65], v149 offset:13824
	ds_read_b128 v[74:77], v145 offset:64512
	ds_read_b128 v[78:81], v0 offset:36928
	ds_read_b128 v[106:109], v0 offset:39232
	ds_read_b128 v[110:113], v147 offset:55360
	ds_read_b128 v[114:117], v147 offset:57664
	ds_read_b128 v[118:121], v147 offset:59968
	ds_read_b128 v[122:125], v147 offset:62272
	ds_read_b128 v[126:129], v147 offset:64576
	ds_read_b128 v[130:133], v149 offset:16128
	ds_read_b128 v[134:137], v150 offset:11584
	ds_read_b128 v[138:141], v150 offset:13888
	ds_read_b128 v[142:145], v150 offset:16192
	s_waitcnt lgkmcnt(14)
	v_mfma_f32_16x16x32_bf16 v[70:73], v[34:37], v[18:21], v[70:73]
	v_mfma_f32_16x16x32_bf16 v[10:13], v[34:37], v[26:29], v[10:13]
	v_mfma_f32_16x16x32_bf16 v[34:37], v[42:45], v[18:21], v[82:85]
	v_mfma_f32_16x16x32_bf16 v[14:17], v[42:45], v[26:29], v[14:17]
	v_mfma_f32_16x16x32_bf16 v[42:45], v[50:53], v[18:21], v[86:89]
	v_mfma_f32_16x16x32_bf16 v[22:25], v[50:53], v[26:29], v[22:25]
	v_mfma_f32_16x16x32_bf16 v[50:53], v[54:57], v[18:21], v[90:93]
	v_mfma_f32_16x16x32_bf16 v[54:57], v[54:57], v[26:29], v[30:33]
	s_waitcnt lgkmcnt(11)
	v_mfma_f32_16x16x32_bf16 v[82:85], v[74:77], v[18:21], v[94:97]
	v_mfma_f32_16x16x32_bf16 v[38:41], v[74:77], v[26:29], v[38:41]
	v_mfma_f32_16x16x32_bf16 v[74:77], v[58:61], v[18:21], v[98:101]
	v_mfma_f32_16x16x32_bf16 v[46:49], v[58:61], v[26:29], v[46:49]
	v_mfma_f32_16x16x32_bf16 v[58:61], v[62:65], v[18:21], v[102:105]
	v_mfma_f32_16x16x32_bf16 v[62:65], v[62:65], v[26:29], v[66:69]
	s_waitcnt lgkmcnt(3)
	v_mfma_f32_16x16x32_bf16 v[2:5], v[130:133], v[18:21], v[2:5]
	v_mfma_f32_16x16x32_bf16 v[66:69], v[130:133], v[26:29], v[6:9]
	v_mfma_f32_16x16x32_bf16 v[70:73], v[110:113], v[78:81], v[70:73]
	v_mfma_f32_16x16x32_bf16 v[30:33], v[110:113], v[106:109], v[10:13]
	v_mfma_f32_16x16x32_bf16 v[86:89], v[114:117], v[78:81], v[34:37]
	v_mfma_f32_16x16x32_bf16 v[26:29], v[114:117], v[106:109], v[14:17]
	v_mfma_f32_16x16x32_bf16 v[42:45], v[118:121], v[78:81], v[42:45]
	v_mfma_f32_16x16x32_bf16 v[22:25], v[118:121], v[106:109], v[22:25]
	v_mfma_f32_16x16x32_bf16 v[50:53], v[122:125], v[78:81], v[50:53]
	v_mfma_f32_16x16x32_bf16 v[18:21], v[122:125], v[106:109], v[54:57]
	v_mfma_f32_16x16x32_bf16 v[54:57], v[126:129], v[78:81], v[82:85]
	v_mfma_f32_16x16x32_bf16 v[14:17], v[126:129], v[106:109], v[38:41]
	s_waitcnt lgkmcnt(2)
	v_mfma_f32_16x16x32_bf16 v[74:77], v[134:137], v[78:81], v[74:77]
	v_mfma_f32_16x16x32_bf16 v[10:13], v[134:137], v[106:109], v[46:49]
	s_waitcnt lgkmcnt(1)
	v_mfma_f32_16x16x32_bf16 v[38:41], v[138:141], v[78:81], v[58:61]
	v_mfma_f32_16x16x32_bf16 v[6:9], v[138:141], v[106:109], v[62:65]
	s_waitcnt lgkmcnt(0)
	v_mfma_f32_16x16x32_bf16 v[34:37], v[142:145], v[78:81], v[2:5]
	v_mfma_f32_16x16x32_bf16 v[2:5], v[142:145], v[106:109], v[66:69]
	v_mov_b32_e32 v0, v179
	v_mov_b32_e32 v46, v179
	s_mov_b64 s[0:1], 0
	s_barrier
	s_add_u32 s8, s90, s0
	s_addc_u32 s9, s91, s1
	s_lshl_b32 s0, s34, 2
	v_readlane_b32 s1, v255, 24
	s_add_u32 s0, s1, s0
	v_readlane_b32 s1, v255, 26
	s_addc_u32 s1, s1, 0
	v_ashrrev_i32_e32 v46, 1, v46
	s_lshl_b32 s10, s34, 1
	v_and_b32_e32 v46, 0xffffffe0, v46
	v_and_or_b32 v47, v0, 15, s35
	s_add_u32 s8, s8, s10
	v_add_u32_e32 v58, v46, v47
	v_lshrrev_b32_e32 v0, 2, v0
	s_addc_u32 s9, s9, 0
	v_and_b32_e32 v0, 12, v0
	s_add_u32 s8, s8, 0x2513d700
	v_ashrrev_i32_e32 v59, 31, v58
	s_addc_u32 s9, s9, 0
	v_lshlrev_b64 v[46:47], 11, v[58:59]
	v_lshlrev_b32_e32 v59, 2, v0
	v_lshl_add_u64 v[60:61], s[8:9], 0, v[46:47]
	global_load_dwordx4 v[90:93], v59, s[0:1]
	global_load_dwordx4 v[94:97], v59, s[0:1] offset:64
	global_load_dwordx4 v[98:101], v59, s[0:1] offset:128
	global_load_dwordx4 v[102:105], v59, s[0:1] offset:192
	global_load_dwordx4 v[106:109], v59, s[0:1] offset:256
	global_load_dwordx4 v[110:113], v59, s[0:1] offset:320
	global_load_dwordx4 v[138:141], v59, s[0:1] offset:384
	global_load_dwordx4 v[142:145], v59, s[0:1] offset:448
	v_lshlrev_b32_e32 v0, 1, v0
	v_lshl_add_u64 v[60:61], v[60:61], 0, v[0:1]
	s_waitcnt vmcnt(7)
	v_mul_f32_e32 v46, v70, v90
	v_mul_f32_e32 v47, v71, v91
	v_mul_f32_e32 v48, v72, v92
	v_mul_f32_e32 v49, v73, v93
	v_cvt_pk_bf16_f32 v46, v46, v47
	v_cvt_pk_bf16_f32 v47, v48, v49
	global_store_dwordx2 v[60:61], v[46:47], off
	s_waitcnt vmcnt(7)
	v_mul_f32_e32 v46, v86, v94
	v_mul_f32_e32 v47, v87, v95
	v_mul_f32_e32 v48, v88, v96
	v_mul_f32_e32 v49, v89, v97
	v_cvt_pk_bf16_f32 v46, v46, v47
	v_cvt_pk_bf16_f32 v47, v48, v49
	global_store_dwordx2 v[60:61], v[46:47], off offset:32
	s_waitcnt vmcnt(7)
	v_mul_f32_e32 v42, v42, v98
	v_mul_f32_e32 v43, v43, v99
	v_mul_f32_e32 v44, v44, v100
	v_mul_f32_e32 v45, v45, v101
	v_cvt_pk_bf16_f32 v42, v42, v43
	v_cvt_pk_bf16_f32 v43, v44, v45
	global_store_dwordx2 v[60:61], v[42:43], off offset:64
	s_waitcnt vmcnt(7)
	v_mul_f32_e32 v42, v50, v102
	v_mul_f32_e32 v43, v51, v103
	v_mul_f32_e32 v44, v52, v104
	v_mul_f32_e32 v45, v53, v105
	v_cvt_pk_bf16_f32 v42, v42, v43
	v_cvt_pk_bf16_f32 v43, v44, v45
	global_store_dwordx2 v[60:61], v[42:43], off offset:96
	s_waitcnt vmcnt(7)
	v_mul_f32_e32 v42, v54, v106
	v_mul_f32_e32 v43, v55, v107
	v_mul_f32_e32 v44, v56, v108
	v_mul_f32_e32 v45, v57, v109
	v_cvt_pk_bf16_f32 v42, v42, v43
	v_cvt_pk_bf16_f32 v43, v44, v45
	global_store_dwordx2 v[60:61], v[42:43], off offset:128
	s_waitcnt vmcnt(7)
	v_mul_f32_e32 v42, v74, v110
	v_mul_f32_e32 v43, v75, v111
	v_mul_f32_e32 v44, v76, v112
	v_mul_f32_e32 v45, v77, v113
	v_cvt_pk_bf16_f32 v42, v42, v43
	v_cvt_pk_bf16_f32 v43, v44, v45
	global_store_dwordx2 v[60:61], v[42:43], off offset:160
	s_waitcnt vmcnt(7)
	v_mul_f32_e32 v38, v38, v138
	v_mul_f32_e32 v39, v39, v139
	v_mul_f32_e32 v40, v40, v140
	v_mul_f32_e32 v41, v41, v141
	v_cvt_pk_bf16_f32 v38, v38, v39
	v_cvt_pk_bf16_f32 v39, v40, v41
	global_store_dwordx2 v[60:61], v[38:39], off offset:192
	s_waitcnt vmcnt(7)
	v_mul_f32_e32 v34, v34, v142
	v_mul_f32_e32 v35, v35, v143
	v_mul_f32_e32 v36, v36, v144
	v_mul_f32_e32 v37, v37, v145
	v_cvt_pk_bf16_f32 v34, v34, v35
	v_cvt_pk_bf16_f32 v35, v36, v37
	global_store_dwordx2 v[60:61], v[34:35], off offset:224
	v_or_b32_e32 v34, 16, v58
	v_ashrrev_i32_e32 v35, 31, v34
	v_lshlrev_b64 v[34:35], 11, v[34:35]
	v_lshl_add_u64 v[38:39], s[8:9], 0, v[34:35]
	global_load_dwordx4 v[146:149], v59, s[0:1]
	global_load_dwordx4 v[150:153], v59, s[0:1] offset:64
	global_load_dwordx4 v[154:157], v59, s[0:1] offset:128
	global_load_dwordx4 v[162:165], v59, s[0:1] offset:192
	global_load_dwordx4 v[166:169], v59, s[0:1] offset:256
	global_load_dwordx4 v[170:173], v59, s[0:1] offset:320
	global_load_dwordx4 v[174:177], v59, s[0:1] offset:384
	global_load_dwordx4 v[194:197], v59, s[0:1] offset:448
	s_waitcnt vmcnt(7)
	v_mul_f32_e32 v30, v30, v146
	v_mul_f32_e32 v31, v31, v147
	v_mul_f32_e32 v32, v32, v148
	v_mul_f32_e32 v33, v33, v149
	v_cvt_pk_bf16_f32 v30, v30, v31
	v_cvt_pk_bf16_f32 v31, v32, v33
	v_lshl_add_u64 v[34:35], v[38:39], 0, v[0:1]
	global_store_dwordx2 v[34:35], v[30:31], off
	s_waitcnt vmcnt(7)
	v_mul_f32_e32 v0, v26, v150
	v_mul_f32_e32 v26, v27, v151
	v_mul_f32_e32 v27, v28, v152
	v_mul_f32_e32 v28, v29, v153
	v_cvt_pk_bf16_f32 v26, v0, v26
	v_cvt_pk_bf16_f32 v27, v27, v28
	global_store_dwordx2 v[34:35], v[26:27], off offset:32
	s_waitcnt vmcnt(7)
	v_mul_f32_e32 v0, v22, v154
	v_mul_f32_e32 v22, v23, v155
	v_mul_f32_e32 v23, v24, v156
	v_mul_f32_e32 v24, v25, v157
	v_cvt_pk_bf16_f32 v22, v0, v22
	v_cvt_pk_bf16_f32 v23, v23, v24
	global_store_dwordx2 v[34:35], v[22:23], off offset:64
	s_waitcnt vmcnt(7)
	v_mul_f32_e32 v0, v18, v162
	v_mul_f32_e32 v18, v19, v163
	v_mul_f32_e32 v19, v20, v164
	v_mul_f32_e32 v20, v21, v165
	v_cvt_pk_bf16_f32 v18, v0, v18
	v_cvt_pk_bf16_f32 v19, v19, v20
	global_store_dwordx2 v[34:35], v[18:19], off offset:96
	s_waitcnt vmcnt(7)
	v_mul_f32_e32 v0, v14, v166
	v_mul_f32_e32 v14, v15, v167
	v_mul_f32_e32 v15, v16, v168
	v_mul_f32_e32 v16, v17, v169
	v_cvt_pk_bf16_f32 v14, v0, v14
	v_cvt_pk_bf16_f32 v15, v15, v16
	global_store_dwordx2 v[34:35], v[14:15], off offset:128
	s_waitcnt vmcnt(7)
	v_mul_f32_e32 v0, v10, v170
	v_mul_f32_e32 v10, v11, v171
	v_mul_f32_e32 v11, v12, v172
	v_mul_f32_e32 v12, v13, v173
	v_cvt_pk_bf16_f32 v10, v0, v10
	v_cvt_pk_bf16_f32 v11, v11, v12
	global_store_dwordx2 v[34:35], v[10:11], off offset:160
	s_waitcnt vmcnt(7)
	v_mul_f32_e32 v0, v6, v174
	v_mul_f32_e32 v6, v7, v175
	v_mul_f32_e32 v7, v8, v176
	v_mul_f32_e32 v8, v9, v177
	v_cvt_pk_bf16_f32 v6, v0, v6
	v_cvt_pk_bf16_f32 v7, v7, v8
	global_store_dwordx2 v[34:35], v[6:7], off offset:192
	s_mov_b64 s[0:1], 0
	s_waitcnt vmcnt(7)
	v_mul_f32_e32 v0, v2, v194
	v_mul_f32_e32 v2, v3, v195
	v_mul_f32_e32 v3, v4, v196
	v_mul_f32_e32 v4, v5, v197
	v_cvt_pk_bf16_f32 v2, v0, v2
	v_cvt_pk_bf16_f32 v3, v3, v4
	global_store_dwordx2 v[34:35], v[2:3], off offset:224
